# diff attention unit epilogue: row stores paired into dwordx4 via permlane32_swap (8 instead of 16 store instructions) on top of the gamma preload
# baseline (speedup 1.0000x reference)
; __device__ __forceinline__ float halfswap_sum(float v) { auto rr = __builtin_amdgcn_permlane32_swap(__float_as_uint(v), __float_as_uint(v), false, false); return __uint_as_float(rr[0]) + __uint_as_float(rr[1]); }
; __device__ __forceinline__ void diff_unit(ALDS unsigned char* ring, const int wid, int lane, const bf16_t* qkv, bf16_t* ymix, const int u, const float lam, const float post, const float* subg, const bool pre, const int u_next) {
;     ...
;     if (comp == 0) {
;         float ss = 0.f;
; #pragma unroll
;         for (int db = 0; db < 4; ++db)
; #pragma unroll
;             for (int rq = 0; rq < 4; ++rq) { const f32x4 o2 = X[(db * 4 + rq) * 64 + lane];
; #pragma unroll
;                 for (int e = 0; e < 4; ++e) { const float d = o[db][4 * rq + e] * inv - lam * o2[e]; o[db][4 * rq + e] = d; ss += d * d; } }
;         ss = halfswap_sum(ss);
;         const float rs = rsqrtf(ss * (1.0f / 128.0f) + 1e-5f) * post;
;         bf16_t* orow = ymix + (rowbase + q0 + r32) * 1024 + h * 128 + 4 * hi;
.LBB0_781:
	v_readlane_b32 s4, v253, 12
	s_waitcnt lgkmcnt(0)
	s_barrier
	v_readlane_b32 s5, v253, 13
	s_andn2_b64 vcc, exec, s[4:5]
	s_cbranch_vccnz .LBB0_765
	ds_read_b128 v[92:95], v66
	ds_read_b128 v[98:101], v66 offset:1024
	ds_read_b128 v[102:105], v66 offset:2048
	ds_read_b128 v[106:109], v66 offset:3072
	ds_read_b128 v[110:113], v66 offset:4096
	ds_read_b128 v[114:117], v66 offset:5120
	ds_read_b128 v[118:121], v66 offset:6144
	ds_read_b128 v[122:125], v66 offset:7168
	ds_read_b128 v[126:129], v66 offset:8192
	ds_read_b128 v[130:133], v66 offset:9216
	ds_read_b128 v[134:137], v66 offset:10240
	ds_read_b128 v[138:141], v66 offset:11264
	ds_read_b128 v[82:85], v66 offset:12288
	ds_read_b128 v[78:81], v66 offset:13312
	ds_read_b128 v[74:77], v66 offset:14336
	ds_read_b128 v[70:73], v66 offset:15360
	s_waitcnt lgkmcnt(14)
	v_pk_mul_f32 v[90:91], v[146:147], v[94:95]
	v_or_b32_e32 v66, s1, v150
	v_pk_fma_f32 v[90:91], v[52:53], v[0:1], v[90:91] op_sel_hi:[1,0,1] neg_lo:[0,0,1] neg_hi:[0,0,1]
	v_pk_mul_f32 v[52:53], v[146:147], v[92:93]
	v_mov_b32_e32 v67, s45
	v_pk_fma_f32 v[92:93], v[50:51], v[0:1], v[52:53] op_sel_hi:[1,0,1] neg_lo:[0,0,1] neg_hi:[0,0,1]
	v_mul_f32_e32 v52, v91, v91
	v_mul_f32_e32 v50, v93, v93
	v_pk_fma_f32 v[50:51], v[92:93], v[92:93], v[50:51] op_sel_hi:[1,1,0]
	v_ashrrev_i32_e32 v68, 3, v149
	v_pk_fma_f32 v[50:51], v[90:91], v[90:91], v[50:51]
	v_lshlrev_b64 v[66:67], 11, v[66:67]
	v_pk_add_f32 v[50:51], v[52:53], v[50:51] op_sel_hi:[0,1]
	v_pk_mul_f32 v[52:53], v[146:147], v[100:101]
	v_and_b32_e32 v68, -4, v68
	v_pk_fma_f32 v[96:97], v[56:57], v[0:1], v[52:53] op_sel_hi:[1,0,1] neg_lo:[0,0,1] neg_hi:[0,0,1]
	v_pk_mul_f32 v[52:53], v[146:147], v[98:99]
	v_lshl_add_u64 v[66:67], s[96:97], 0, v[66:67]
	v_pk_fma_f32 v[98:99], v[54:55], v[0:1], v[52:53] op_sel_hi:[1,0,1] neg_lo:[0,0,1] neg_hi:[0,0,1]
	v_ashrrev_i32_e32 v69, 31, v68
	v_pk_fma_f32 v[50:51], v[98:99], v[98:99], v[50:51]
	v_mul_f32_e32 v52, v99, v99
	v_pk_add_f32 v[50:51], v[52:53], v[50:51] op_sel_hi:[0,1]
	v_pk_fma_f32 v[50:51], v[96:97], v[96:97], v[50:51]
	v_mul_f32_e32 v52, v97, v97
	v_pk_add_f32 v[50:51], v[52:53], v[50:51] op_sel_hi:[0,1]
	s_waitcnt lgkmcnt(13)
	v_pk_mul_f32 v[52:53], v[146:147], v[104:105]
	v_lshl_add_u64 v[66:67], v[66:67], 0, s[76:77]
	v_pk_fma_f32 v[94:95], v[60:61], v[0:1], v[52:53] op_sel_hi:[1,0,1] neg_lo:[0,0,1] neg_hi:[0,0,1]
	v_pk_mul_f32 v[52:53], v[146:147], v[102:103]
	v_lshl_add_u64 v[88:89], v[68:69], 2, s[42:43]
	v_pk_fma_f32 v[100:101], v[58:59], v[0:1], v[52:53] op_sel_hi:[1,0,1] neg_lo:[0,0,1] neg_hi:[0,0,1]
	v_lshl_add_u64 v[86:87], v[68:69], 2, v[66:67]
	v_pk_fma_f32 v[50:51], v[100:101], v[100:101], v[50:51]
	v_mul_f32_e32 v52, v101, v101
	v_pk_add_f32 v[50:51], v[52:53], v[50:51] op_sel_hi:[0,1]
	v_pk_fma_f32 v[50:51], v[94:95], v[94:95], v[50:51]
	v_mul_f32_e32 v52, v95, v95
	v_pk_add_f32 v[50:51], v[52:53], v[50:51] op_sel_hi:[0,1]
	s_waitcnt lgkmcnt(12)
	v_pk_mul_f32 v[52:53], v[146:147], v[108:109]
	v_pk_fma_f32 v[60:61], v[64:65], v[0:1], v[52:53] op_sel_hi:[1,0,1] neg_lo:[0,0,1] neg_hi:[0,0,1]
	v_pk_mul_f32 v[52:53], v[146:147], v[106:107]
	s_nop 0
	v_pk_fma_f32 v[64:65], v[62:63], v[0:1], v[52:53] op_sel_hi:[1,0,1] neg_lo:[0,0,1] neg_hi:[0,0,1]
	s_nop 0
	v_pk_fma_f32 v[50:51], v[64:65], v[64:65], v[50:51]
	v_mul_f32_e32 v52, v65, v65
	v_pk_add_f32 v[50:51], v[52:53], v[50:51] op_sel_hi:[0,1]
	v_pk_fma_f32 v[50:51], v[60:61], v[60:61], v[50:51]
	v_mul_f32_e32 v52, v61, v61
	v_pk_add_f32 v[50:51], v[52:53], v[50:51] op_sel_hi:[0,1]
	s_waitcnt lgkmcnt(11)
	v_pk_mul_f32 v[52:53], v[146:147], v[112:113]
	s_nop 0
	v_pk_fma_f32 v[56:57], v[36:37], v[0:1], v[52:53] op_sel_hi:[1,0,1] neg_lo:[0,0,1] neg_hi:[0,0,1]
	v_pk_mul_f32 v[36:37], v[146:147], v[110:111]
	s_nop 0
	v_pk_fma_f32 v[62:63], v[34:35], v[0:1], v[36:37] op_sel_hi:[1,0,1] neg_lo:[0,0,1] neg_hi:[0,0,1]
	s_nop 0
	v_pk_fma_f32 v[34:35], v[62:63], v[62:63], v[50:51]
	v_mul_f32_e32 v36, v63, v63
	v_pk_add_f32 v[34:35], v[36:37], v[34:35] op_sel_hi:[0,1]
	v_pk_fma_f32 v[34:35], v[56:57], v[56:57], v[34:35]
	v_mul_f32_e32 v36, v57, v57
	v_pk_add_f32 v[34:35], v[36:37], v[34:35] op_sel_hi:[0,1]
	s_waitcnt lgkmcnt(10)
	v_pk_mul_f32 v[36:37], v[146:147], v[116:117]
	s_nop 0
	v_pk_fma_f32 v[52:53], v[40:41], v[0:1], v[36:37] op_sel_hi:[1,0,1] neg_lo:[0,0,1] neg_hi:[0,0,1]
	v_pk_mul_f32 v[36:37], v[146:147], v[114:115]
	s_nop 0
	v_pk_fma_f32 v[58:59], v[38:39], v[0:1], v[36:37] op_sel_hi:[1,0,1] neg_lo:[0,0,1] neg_hi:[0,0,1]
	s_nop 0
	v_pk_fma_f32 v[34:35], v[58:59], v[58:59], v[34:35]
	v_mul_f32_e32 v36, v59, v59
	v_pk_add_f32 v[34:35], v[36:37], v[34:35] op_sel_hi:[0,1]
	v_pk_fma_f32 v[34:35], v[52:53], v[52:53], v[34:35]
	v_mul_f32_e32 v36, v53, v53
	v_pk_add_f32 v[34:35], v[36:37], v[34:35] op_sel_hi:[0,1]
	s_waitcnt lgkmcnt(9)
	v_pk_mul_f32 v[36:37], v[146:147], v[120:121]
	s_nop 0
	v_pk_fma_f32 v[50:51], v[44:45], v[0:1], v[36:37] op_sel_hi:[1,0,1] neg_lo:[0,0,1] neg_hi:[0,0,1]
	v_pk_mul_f32 v[36:37], v[146:147], v[118:119]
	s_nop 0
	v_pk_fma_f32 v[54:55], v[42:43], v[0:1], v[36:37] op_sel_hi:[1,0,1] neg_lo:[0,0,1] neg_hi:[0,0,1]
	s_nop 0
	v_pk_fma_f32 v[34:35], v[54:55], v[54:55], v[34:35]
	v_mul_f32_e32 v36, v55, v55
	v_pk_add_f32 v[34:35], v[36:37], v[34:35] op_sel_hi:[0,1]
	v_pk_fma_f32 v[34:35], v[50:51], v[50:51], v[34:35]
	v_mul_f32_e32 v36, v51, v51
	v_pk_add_f32 v[34:35], v[36:37], v[34:35] op_sel_hi:[0,1]
	s_waitcnt lgkmcnt(8)
; __device__ __forceinline__ void diff_unit(ALDS unsigned char* ring, const int wid, int lane, const bf16_t* qkv, bf16_t* ymix, const int u, const float lam, const float post, const float* subg, const bool pre, const int u_next) {
;     ...
;             for (int rq = 0; rq < 4; ++rq) { const f32x4 o2 = X[(db * 4 + rq) * 64 + lane];
; #pragma unroll
;                 for (int e = 0; e < 4; ++e) { const float d = o[db][4 * rq + e] * inv - lam * o2[e]; o[db][4 * rq + e] = d; ss += d * d; } }
	v_pk_mul_f32 v[36:37], v[146:147], v[124:125]
	s_nop 0
	v_pk_fma_f32 v[42:43], v[48:49], v[0:1], v[36:37] op_sel_hi:[1,0,1] neg_lo:[0,0,1] neg_hi:[0,0,1]
	v_pk_mul_f32 v[36:37], v[146:147], v[122:123]
	s_nop 0
	v_pk_fma_f32 v[46:47], v[46:47], v[0:1], v[36:37] op_sel_hi:[1,0,1] neg_lo:[0,0,1] neg_hi:[0,0,1]
	s_nop 0
	v_pk_fma_f32 v[34:35], v[46:47], v[46:47], v[34:35]
	v_mul_f32_e32 v36, v47, v47
	v_pk_add_f32 v[34:35], v[36:37], v[34:35] op_sel_hi:[0,1]
	v_pk_fma_f32 v[34:35], v[42:43], v[42:43], v[34:35]
	v_mul_f32_e32 v36, v43, v43
	v_pk_add_f32 v[34:35], v[36:37], v[34:35] op_sel_hi:[0,1]
	s_waitcnt lgkmcnt(7)
	v_pk_mul_f32 v[36:37], v[146:147], v[128:129]
	s_nop 0
	v_pk_fma_f32 v[38:39], v[20:21], v[0:1], v[36:37] op_sel_hi:[1,0,1] neg_lo:[0,0,1] neg_hi:[0,0,1]
	v_pk_mul_f32 v[20:21], v[146:147], v[126:127]
	s_nop 0
	v_pk_fma_f32 v[44:45], v[18:19], v[0:1], v[20:21] op_sel_hi:[1,0,1] neg_lo:[0,0,1] neg_hi:[0,0,1]
	s_nop 0
	v_pk_fma_f32 v[18:19], v[44:45], v[44:45], v[34:35]
	v_mul_f32_e32 v20, v45, v45
	v_pk_add_f32 v[18:19], v[20:21], v[18:19] op_sel_hi:[0,1]
	v_pk_fma_f32 v[18:19], v[38:39], v[38:39], v[18:19]
	v_mul_f32_e32 v20, v39, v39
	v_pk_add_f32 v[18:19], v[20:21], v[18:19] op_sel_hi:[0,1]
	s_waitcnt lgkmcnt(6)
	v_pk_mul_f32 v[20:21], v[146:147], v[132:133]
	s_nop 0
	v_pk_fma_f32 v[34:35], v[24:25], v[0:1], v[20:21] op_sel_hi:[1,0,1] neg_lo:[0,0,1] neg_hi:[0,0,1]
	v_pk_mul_f32 v[20:21], v[146:147], v[130:131]
	s_nop 0
	v_pk_fma_f32 v[40:41], v[22:23], v[0:1], v[20:21] op_sel_hi:[1,0,1] neg_lo:[0,0,1] neg_hi:[0,0,1]
	s_nop 0
	v_pk_fma_f32 v[18:19], v[40:41], v[40:41], v[18:19]
	v_mul_f32_e32 v20, v41, v41
	v_pk_add_f32 v[18:19], v[20:21], v[18:19] op_sel_hi:[0,1]
	v_pk_fma_f32 v[18:19], v[34:35], v[34:35], v[18:19]
	v_mul_f32_e32 v20, v35, v35
	v_pk_add_f32 v[18:19], v[20:21], v[18:19] op_sel_hi:[0,1]
	s_waitcnt lgkmcnt(5)
	v_pk_mul_f32 v[20:21], v[146:147], v[136:137]
	s_nop 0
	v_pk_fma_f32 v[28:29], v[28:29], v[0:1], v[20:21] op_sel_hi:[1,0,1] neg_lo:[0,0,1] neg_hi:[0,0,1]
	v_pk_mul_f32 v[20:21], v[146:147], v[134:135]
	s_nop 0
	v_pk_fma_f32 v[36:37], v[26:27], v[0:1], v[20:21] op_sel_hi:[1,0,1] neg_lo:[0,0,1] neg_hi:[0,0,1]
	s_nop 0
	v_pk_fma_f32 v[18:19], v[36:37], v[36:37], v[18:19]
	v_mul_f32_e32 v20, v37, v37
	v_pk_add_f32 v[18:19], v[20:21], v[18:19] op_sel_hi:[0,1]
	v_pk_fma_f32 v[18:19], v[28:29], v[28:29], v[18:19]
	v_mul_f32_e32 v20, v29, v29
	v_pk_add_f32 v[18:19], v[20:21], v[18:19] op_sel_hi:[0,1]
	s_waitcnt lgkmcnt(4)
	v_pk_mul_f32 v[20:21], v[146:147], v[140:141]
	s_nop 0
	v_pk_fma_f32 v[22:23], v[32:33], v[0:1], v[20:21] op_sel_hi:[1,0,1] neg_lo:[0,0,1] neg_hi:[0,0,1]
	v_pk_mul_f32 v[20:21], v[146:147], v[138:139]
	s_nop 0
	v_pk_fma_f32 v[26:27], v[30:31], v[0:1], v[20:21] op_sel_hi:[1,0,1] neg_lo:[0,0,1] neg_hi:[0,0,1]
	s_nop 0
	v_pk_fma_f32 v[18:19], v[26:27], v[26:27], v[18:19]
	v_mul_f32_e32 v20, v27, v27
	v_pk_add_f32 v[18:19], v[20:21], v[18:19] op_sel_hi:[0,1]
	v_pk_fma_f32 v[18:19], v[22:23], v[22:23], v[18:19]
	v_mul_f32_e32 v20, v23, v23
	v_pk_add_f32 v[20:21], v[20:21], v[18:19] op_sel_hi:[0,1]
	s_waitcnt lgkmcnt(3)
	v_pk_mul_f32 v[18:19], v[146:147], v[84:85]
	s_nop 0
	v_pk_fma_f32 v[18:19], v[4:5], v[0:1], v[18:19] op_sel_hi:[1,0,1] neg_lo:[0,0,1] neg_hi:[0,0,1]
	v_pk_mul_f32 v[4:5], v[146:147], v[82:83]
	s_nop 0
	v_pk_fma_f32 v[24:25], v[2:3], v[0:1], v[4:5] op_sel_hi:[1,0,1] neg_lo:[0,0,1] neg_hi:[0,0,1]
	s_nop 0
	v_pk_fma_f32 v[2:3], v[24:25], v[24:25], v[20:21]
	v_mul_f32_e32 v4, v25, v25
	v_pk_add_f32 v[2:3], v[4:5], v[2:3] op_sel_hi:[0,1]
	v_pk_fma_f32 v[2:3], v[18:19], v[18:19], v[2:3]
	v_mul_f32_e32 v4, v19, v19
	v_pk_add_f32 v[2:3], v[4:5], v[2:3] op_sel_hi:[0,1]
	s_waitcnt lgkmcnt(2)
	v_pk_mul_f32 v[4:5], v[146:147], v[80:81]
	s_nop 0
	v_pk_fma_f32 v[8:9], v[8:9], v[0:1], v[4:5] op_sel_hi:[1,0,1] neg_lo:[0,0,1] neg_hi:[0,0,1]
	v_pk_mul_f32 v[4:5], v[146:147], v[78:79]
	s_nop 0
	v_pk_fma_f32 v[20:21], v[6:7], v[0:1], v[4:5] op_sel_hi:[1,0,1] neg_lo:[0,0,1] neg_hi:[0,0,1]
	s_waitcnt lgkmcnt(1)
	v_pk_mul_f32 v[6:7], v[146:147], v[74:75]
	v_pk_fma_f32 v[2:3], v[20:21], v[20:21], v[2:3]
	v_mul_f32_e32 v4, v21, v21
	v_pk_add_f32 v[2:3], v[4:5], v[2:3] op_sel_hi:[0,1]
	v_pk_fma_f32 v[2:3], v[8:9], v[8:9], v[2:3]
	v_mul_f32_e32 v4, v9, v9
	v_pk_add_f32 v[2:3], v[4:5], v[2:3] op_sel_hi:[0,1]
	v_pk_fma_f32 v[10:11], v[10:11], v[0:1], v[6:7] op_sel_hi:[1,0,1] neg_lo:[0,0,1] neg_hi:[0,0,1]
	v_pk_mul_f32 v[4:5], v[146:147], v[76:77]
	v_pk_fma_f32 v[2:3], v[10:11], v[10:11], v[2:3]
	v_mul_f32_e32 v6, v11, v11
	v_pk_fma_f32 v[4:5], v[12:13], v[0:1], v[4:5] op_sel_hi:[1,0,1] neg_lo:[0,0,1] neg_hi:[0,0,1]
	v_pk_add_f32 v[2:3], v[6:7], v[2:3] op_sel_hi:[0,1]
	v_pk_fma_f32 v[2:3], v[4:5], v[4:5], v[2:3]
	v_mul_f32_e32 v6, v5, v5
	v_pk_add_f32 v[12:13], v[6:7], v[2:3] op_sel_hi:[0,1]
	s_waitcnt lgkmcnt(0)
; __device__ __forceinline__ unsigned cvtpk(float lo, float hi) { f32x2_t v = {lo, hi}; bf16x2_t b = __builtin_convertvector(v, bf16x2_t); return __builtin_bit_cast(unsigned, b); }
; __device__ __forceinline__ float halfswap_sum(float v) { auto rr = __builtin_amdgcn_permlane32_swap(__float_as_uint(v), __float_as_uint(v), false, false); return __uint_as_float(rr[0]) + __uint_as_float(rr[1]); }
; __device__ __forceinline__ void diff_unit(ALDS unsigned char* ring, const int wid, int lane, const bf16_t* qkv, bf16_t* ymix, const int u, const float lam, const float post, const float* subg, const bool pre, const int u_next) {
;     ...
;         ss = halfswap_sum(ss);
;         const float rs = rsqrtf(ss * (1.0f / 128.0f) + 1e-5f) * post;
;         bf16_t* orow = ymix + (rowbase + q0 + r32) * 1024 + h * 128 + 4 * hi;
; #pragma unroll
;         for (int db = 0; db < 4; ++db)
; #pragma unroll
;             for (int rq = 0; rq < 4; ++rq) { const f32x4 gv = *(const f32x4*)(subg + 32 * db + 8 * rq + 4 * hi);
;                 u32x2 w; w.x = cvtpk(o[db][4 * rq] * rs * gv[0], o[db][4 * rq + 1] * rs * gv[1]); w.y = cvtpk(o[db][4 * rq + 2] * rs * gv[2], o[db][4 * rq + 3] * rs * gv[3]);
;                 *(u32x2*)(orow + 32 * db + 8 * rq) = w; }
	v_pk_mul_f32 v[6:7], v[146:147], v[70:71]
	v_pk_mul_f32 v[2:3], v[146:147], v[72:73]
	v_pk_fma_f32 v[6:7], v[14:15], v[0:1], v[6:7] op_sel_hi:[1,0,1] neg_lo:[0,0,1] neg_hi:[0,0,1]
	v_pk_fma_f32 v[2:3], v[16:17], v[0:1], v[2:3] op_sel_hi:[1,0,1] neg_lo:[0,0,1] neg_hi:[0,0,1]
	v_pk_fma_f32 v[12:13], v[6:7], v[6:7], v[12:13]
	v_mul_f32_e32 v0, v7, v7
	v_pk_add_f32 v[12:13], v[0:1], v[12:13] op_sel_hi:[0,1]
	v_pk_fma_f32 v[12:13], v[2:3], v[2:3], v[12:13]
	v_mul_f32_e32 v0, v3, v3
	v_pk_add_f32 v[12:13], v[0:1], v[12:13] op_sel_hi:[0,1]
	v_mov_b32_e32 v0, v12
	s_nop 1
	v_permlane32_swap_b32_e32 v12, v0
	v_add_f32_e32 v0, v12, v0
	v_mov_b32_e32 v12, 0x3727c5ac
	v_fmamk_f32 v0, v0, 0x3c000000, v12
	v_cmp_gt_f32_e32 vcc, s29, v0
	v_mul_f32_e32 v12, 0x4b800000, v0
	s_nop 0
	v_cndmask_b32_e32 v0, v0, v12, vcc
	v_rsq_f32_e32 v0, v0
	s_nop 0
	v_mul_f32_e32 v12, 0x45800000, v0
	v_cndmask_b32_e32 v0, v0, v12, vcc
	v_mul_f32_e32 v0, v148, v0
	v_pk_mul_f32 v[12:13], v[92:93], v[0:1] op_sel_hi:[1,0]
	v_pk_mul_f32 v[14:15], v[90:91], v[0:1] op_sel_hi:[1,0]
	v_pk_mul_f32 v[12:13], v[178:179], v[12:13]
	v_pk_mul_f32 v[14:15], v[180:181], v[14:15]
	v_cvt_pk_bf16_f32 v248, v12, v13
	v_cvt_pk_bf16_f32 v249, v14, v15
	s_nop 0
	v_pk_mul_f32 v[16:17], v[98:99], v[0:1] op_sel_hi:[1,0]
	v_pk_mul_f32 v[8:9], v[8:9], v[0:1] op_sel_hi:[1,0]
	v_pk_mul_f32 v[4:5], v[4:5], v[0:1] op_sel_hi:[1,0]
	v_pk_mul_f32 v[2:3], v[2:3], v[0:1] op_sel_hi:[1,0]
	v_pk_mul_f32 v[12:13], v[182:183], v[16:17]
	v_pk_mul_f32 v[16:17], v[96:97], v[0:1] op_sel_hi:[1,0]
	v_cvt_pk_bf16_f32 v250, v12, v13
	v_pk_mul_f32 v[14:15], v[184:185], v[16:17]
	v_pk_mul_f32 v[16:17], v[100:101], v[0:1] op_sel_hi:[1,0]
	v_cvt_pk_bf16_f32 v251, v14, v15
	s_nop 1
	v_permlane32_swap_b32_e32 v248, v250
	v_permlane32_swap_b32_e32 v249, v251
	global_store_dwordx4 v[86:87], v[248:251], off
	v_pk_mul_f32 v[12:13], v[186:187], v[16:17]
	v_pk_mul_f32 v[16:17], v[94:95], v[0:1] op_sel_hi:[1,0]
	v_cvt_pk_bf16_f32 v248, v12, v13
	v_pk_mul_f32 v[14:15], v[188:189], v[16:17]
	v_pk_mul_f32 v[16:17], v[64:65], v[0:1] op_sel_hi:[1,0]
	v_cvt_pk_bf16_f32 v249, v14, v15
	s_nop 0
	v_pk_mul_f32 v[12:13], v[190:191], v[16:17]
	v_pk_mul_f32 v[16:17], v[60:61], v[0:1] op_sel_hi:[1,0]
	v_cvt_pk_bf16_f32 v250, v12, v13
	v_pk_mul_f32 v[14:15], v[192:193], v[16:17]
	v_pk_mul_f32 v[16:17], v[62:63], v[0:1] op_sel_hi:[1,0]
	v_cvt_pk_bf16_f32 v251, v14, v15
	s_nop 1
	v_permlane32_swap_b32_e32 v248, v250
	v_permlane32_swap_b32_e32 v249, v251
	global_store_dwordx4 v[86:87], v[248:251], off offset:32
	v_pk_mul_f32 v[12:13], v[194:195], v[16:17]
	v_pk_mul_f32 v[16:17], v[56:57], v[0:1] op_sel_hi:[1,0]
	v_cvt_pk_bf16_f32 v248, v12, v13
	v_pk_mul_f32 v[14:15], v[196:197], v[16:17]
	v_pk_mul_f32 v[16:17], v[58:59], v[0:1] op_sel_hi:[1,0]
	v_cvt_pk_bf16_f32 v249, v14, v15
	s_nop 0
	v_pk_mul_f32 v[12:13], v[198:199], v[16:17]
	v_pk_mul_f32 v[16:17], v[52:53], v[0:1] op_sel_hi:[1,0]
	v_cvt_pk_bf16_f32 v250, v12, v13
	v_pk_mul_f32 v[14:15], v[200:201], v[16:17]
	v_pk_mul_f32 v[16:17], v[54:55], v[0:1] op_sel_hi:[1,0]
	v_cvt_pk_bf16_f32 v251, v14, v15
	s_nop 1
	v_permlane32_swap_b32_e32 v248, v250
	v_permlane32_swap_b32_e32 v249, v251
	global_store_dwordx4 v[86:87], v[248:251], off offset:64
	v_pk_mul_f32 v[12:13], v[16:17], v[202:203]
	v_pk_mul_f32 v[16:17], v[50:51], v[0:1] op_sel_hi:[1,0]
	v_cvt_pk_bf16_f32 v248, v12, v13
	v_pk_mul_f32 v[14:15], v[16:17], v[204:205]
	v_pk_mul_f32 v[16:17], v[46:47], v[0:1] op_sel_hi:[1,0]
	v_cvt_pk_bf16_f32 v249, v14, v15
	s_nop 0
	v_pk_mul_f32 v[12:13], v[16:17], v[210:211]
	v_pk_mul_f32 v[16:17], v[42:43], v[0:1] op_sel_hi:[1,0]
	v_cvt_pk_bf16_f32 v250, v12, v13
	v_pk_mul_f32 v[14:15], v[16:17], v[212:213]
	v_pk_mul_f32 v[16:17], v[44:45], v[0:1] op_sel_hi:[1,0]
	v_cvt_pk_bf16_f32 v251, v14, v15
	s_nop 1
	v_permlane32_swap_b32_e32 v248, v250
	v_permlane32_swap_b32_e32 v249, v251
	global_store_dwordx4 v[86:87], v[248:251], off offset:96
	v_pk_mul_f32 v[12:13], v[16:17], v[214:215]
	v_pk_mul_f32 v[16:17], v[38:39], v[0:1] op_sel_hi:[1,0]
	v_cvt_pk_bf16_f32 v248, v12, v13
	v_pk_mul_f32 v[14:15], v[16:17], v[216:217]
	v_pk_mul_f32 v[16:17], v[40:41], v[0:1] op_sel_hi:[1,0]
	v_cvt_pk_bf16_f32 v249, v14, v15
	s_nop 0
	v_pk_mul_f32 v[12:13], v[16:17], v[218:219]
	v_pk_mul_f32 v[16:17], v[34:35], v[0:1] op_sel_hi:[1,0]
	v_cvt_pk_bf16_f32 v250, v12, v13
	v_pk_mul_f32 v[14:15], v[16:17], v[220:221]
	v_pk_mul_f32 v[16:17], v[36:37], v[0:1] op_sel_hi:[1,0]
	v_cvt_pk_bf16_f32 v251, v14, v15
	s_nop 1
	v_permlane32_swap_b32_e32 v248, v250
	v_permlane32_swap_b32_e32 v249, v251
	global_store_dwordx4 v[86:87], v[248:251], off offset:128
	v_pk_mul_f32 v[12:13], v[16:17], v[222:223]
	v_pk_mul_f32 v[16:17], v[28:29], v[0:1] op_sel_hi:[1,0]
	v_cvt_pk_bf16_f32 v248, v12, v13
	v_pk_mul_f32 v[14:15], v[16:17], v[224:225]
	v_pk_mul_f32 v[16:17], v[26:27], v[0:1] op_sel_hi:[1,0]
	v_cvt_pk_bf16_f32 v249, v14, v15
	s_nop 0
	v_pk_mul_f32 v[12:13], v[16:17], v[226:227]
	v_pk_mul_f32 v[16:17], v[22:23], v[0:1] op_sel_hi:[1,0]
	v_cvt_pk_bf16_f32 v250, v12, v13
	v_pk_mul_f32 v[14:15], v[16:17], v[228:229]
	v_pk_mul_f32 v[16:17], v[24:25], v[0:1] op_sel_hi:[1,0]
	v_cvt_pk_bf16_f32 v251, v14, v15
	s_nop 1
	v_permlane32_swap_b32_e32 v248, v250
	v_permlane32_swap_b32_e32 v249, v251
	global_store_dwordx4 v[86:87], v[248:251], off offset:160
	v_pk_mul_f32 v[12:13], v[16:17], v[232:233]
	v_pk_mul_f32 v[16:17], v[18:19], v[0:1] op_sel_hi:[1,0]
	v_cvt_pk_bf16_f32 v248, v12, v13
	v_pk_mul_f32 v[14:15], v[16:17], v[234:235]
	v_pk_mul_f32 v[16:17], v[20:21], v[0:1] op_sel_hi:[1,0]
	v_cvt_pk_bf16_f32 v249, v14, v15
	s_nop 0
	v_pk_mul_f32 v[12:13], v[16:17], v[236:237]
	v_pk_mul_f32 v[8:9], v[8:9], v[238:239]
	v_cvt_pk_bf16_f32 v250, v12, v13
	v_cvt_pk_bf16_f32 v251, v8, v9
	s_nop 1
	v_permlane32_swap_b32_e32 v248, v250
	v_permlane32_swap_b32_e32 v249, v251
	global_store_dwordx4 v[86:87], v[248:251], off offset:192
	v_pk_mul_f32 v[8:9], v[10:11], v[0:1] op_sel_hi:[1,0]
	v_pk_mul_f32 v[4:5], v[4:5], v[242:243]
	v_pk_mul_f32 v[8:9], v[8:9], v[240:241]
	s_nop 0
	v_cvt_pk_bf16_f32 v248, v8, v9
	v_cvt_pk_bf16_f32 v249, v4, v5
	s_nop 0
	v_pk_mul_f32 v[4:5], v[6:7], v[0:1] op_sel_hi:[1,0]
	v_pk_mul_f32 v[2:3], v[2:3], v[246:247]
	v_pk_mul_f32 v[4:5], v[4:5], v[244:245]
	s_nop 0
	v_cvt_pk_bf16_f32 v250, v4, v5
	v_cvt_pk_bf16_f32 v251, v2, v3
	s_nop 1
	v_permlane32_swap_b32_e32 v248, v250
	v_permlane32_swap_b32_e32 v249, v251
	global_store_dwordx4 v[86:87], v[248:251], off offset:224
	s_branch .LBB0_765
